# P5 FFN-in epilogue: 8 rss loads hoisted, counted vmcnt(7) instead of vmcnt(0) per row block (stores no longer drained)
# speedup vs baseline: 1.0083x; 1.0083x over previous
; __device__ __forceinline__ float fast_sigmoid(float z) { return __builtin_amdgcn_rcpf(1.f + __builtin_amdgcn_exp2f(-z * L2E)); }
; __device__ __forceinline__ u32x4 pack8(f32x4 a, f32x4 b) { u32x4 w; w.x = cvt_pk_bf16(a[0], a[1]); w.y = cvt_pk_bf16(a[2], a[3]); w.z = cvt_pk_bf16(b[0], b[1]); w.w = cvt_pk_bf16(b[2], b[3]); return w; }
;     __device__ __forceinline__ void operator()(const f32x4 (&acc)[2][2][4][2], const pg8::Unit& u, int wr, int wc, int fr, int fq) const {
; #pragma unroll
;         for (int ai = 0; ai < 2; ++ai)
; #pragma unroll
;             for (int m = 0; m < 4; ++m) { const int row = u.pm * 256 + ai * 128 + wr * 64 + m * 16 + fr;
;                 const float rstd = __builtin_amdgcn_rsqf(rss[row] * (1.f / D) + EPS);
;                 f32x4 h0, h1;
; #pragma unroll
;                 for (int i = 0; i < 4; ++i) { const float g0 = acc[ai][0][m][0][i] * rstd, u0 = acc[ai][1][m][0][i] * rstd, g1 = acc[ai][0][m][1][i] * rstd, u1 = acc[ai][1][m][1][i] * rstd;
;                     h0[i] = g0 * fast_sigmoid(g0) * u0; h1[i] = g1 * fast_sigmoid(g1) * u1; }
;                 *(u32x4*)(HFF + (size_t)row * DFF + u.pn * 128 + wc * 32 + 8 * fq) = pack8(h0, h1); }
.LBB0_859:
	v_lshl_add_u32 v150, s22, 8, v133
	v_ashrrev_i32_e32 v151, 31, v150
	v_lshl_add_u64 v[156:157], v[150:151], 2, s[6:7]
	global_load_dword v228, v[156:157], off
	global_load_dword v229, v[156:157], off offset:64
	global_load_dword v230, v[156:157], off offset:128
	global_load_dword v231, v[156:157], off offset:192
	global_load_dword v232, v[156:157], off offset:512
	global_load_dword v233, v[156:157], off offset:576
	global_load_dword v234, v[156:157], off offset:640
	global_load_dword v235, v[156:157], off offset:704
	v_mov_b32_e32 v156, v124
	v_mov_b32_e32 v157, v116
	v_mov_b32_e32 v159, v112
	v_mov_b32_e32 v116, v125
	v_mov_b32_e32 v112, v121
	v_mov_b32_e32 v124, v126
	v_mov_b32_e32 v125, v118
	v_mov_b32_e32 v161, v114
	v_mov_b32_e32 v114, v123
	v_mov_b32_e32 v158, v120
	v_mov_b32_e32 v160, v122
	v_mov_b32_e32 v118, v127
	v_or_b32_e32 v126, 16, v150
	v_ashrrev_i32_e32 v127, 31, v126
	v_lshl_add_u64 v[164:165], v[126:127], 2, s[6:7]
	s_lshl_b32 s22, s23, 7
	v_mov_b64_e32 v[120:121], s[8:9]
	s_ashr_i32 s23, s22, 31
	v_mad_i64_i32 v[122:123], s[24:25], v150, s49, v[120:121]
	s_lshl_b64 s[22:23], s[22:23], 1
	v_lshl_add_u64 v[122:123], v[122:123], 0, s[22:23]
	v_lshl_add_u64 v[122:123], v[122:123], 0, s[0:1]
	v_lshl_add_u64 v[122:123], v[122:123], 0, v[140:141]
	s_andn2_b64 vcc, exec, s[2:3]
	s_mov_b64 s[2:3], -1
	s_waitcnt vmcnt(7)
	v_fmamk_f32 v151, v228, 0x3a800000, v155
	v_rsq_f32_e32 v162, v151
	s_nop 0
	v_pk_mul_f32 v[116:117], v[116:117], v[162:163] op_sel_hi:[1,0]
	v_pk_mul_f32 v[112:113], v[112:113], v[162:163] op_sel_hi:[1,0]
	v_pk_mul_f32 v[124:125], v[124:125], v[162:163] op_sel_hi:[1,0]
	v_pk_mul_f32 v[114:115], v[114:115], v[162:163] op_sel_hi:[1,0]
	v_pk_mul_f32 v[156:157], v[156:157], v[162:163] op_sel_hi:[1,0]
	v_pk_mul_f32 v[158:159], v[158:159], v[162:163] op_sel_hi:[1,0]
	v_pk_mul_f32 v[160:161], v[160:161], v[162:163] op_sel_hi:[1,0]
	v_pk_mul_f32 v[118:119], v[118:119], v[162:163] op_sel_hi:[1,0]
	v_mul_f32_e32 v162, 0xbfb8aa3b, v117
	v_mul_f32_e32 v163, 0xbfb8aa3b, v113
	v_mul_f32_e32 v166, 0xbfb8aa3b, v125
	v_mul_f32_e32 v169, 0xbfb8aa3b, v115
	v_mul_f32_e32 v127, 0xbfb8aa3b, v157
	v_mul_f32_e32 v151, 0xbfb8aa3b, v159
	v_mul_f32_e32 v167, 0xbfb8aa3b, v161
	v_mul_f32_e32 v168, 0xbfb8aa3b, v119
	v_exp_f32_e32 v162, v162
	v_exp_f32_e32 v163, v163
	v_exp_f32_e32 v166, v166
	v_exp_f32_e32 v169, v169
	v_exp_f32_e32 v127, v127
	v_exp_f32_e32 v151, v151
	v_exp_f32_e32 v167, v167
	v_exp_f32_e32 v168, v168
	v_add_f32_e32 v162, 1.0, v162
	v_add_f32_e32 v163, 1.0, v163
	v_add_f32_e32 v166, 1.0, v166
	v_add_f32_e32 v169, 1.0, v169
	v_add_f32_e32 v127, 1.0, v127
	v_add_f32_e32 v151, 1.0, v151
	v_add_f32_e32 v167, 1.0, v167
	v_add_f32_e32 v168, 1.0, v168
	v_rcp_f32_e32 v162, v162
	v_rcp_f32_e32 v163, v163
	v_rcp_f32_e32 v166, v166
	v_rcp_f32_e32 v169, v169
	v_rcp_f32_e32 v127, v127
	v_rcp_f32_e32 v151, v151
	v_rcp_f32_e32 v167, v167
	v_rcp_f32_e32 v168, v168
	v_mul_f32_e32 v117, v117, v162
	v_mul_f32_e32 v113, v113, v163
	v_mul_f32_e32 v125, v125, v166
	v_mul_f32_e32 v115, v115, v169
	v_mul_f32_e32 v127, v157, v127
	v_mul_f32_e32 v151, v159, v151
	v_mul_f32_e32 v157, v161, v167
	v_mul_f32_e32 v119, v119, v168
	v_mul_f32_e32 v116, v116, v117
	v_mul_f32_e32 v117, v112, v113
	v_mul_f32_e32 v113, v124, v125
	v_mul_f32_e32 v115, v114, v115
	v_mul_f32_e32 v127, v156, v127
	v_mul_f32_e32 v151, v158, v151
	v_mul_f32_e32 v124, v160, v157
	v_mul_f32_e32 v118, v118, v119
	v_cvt_pk_bf16_f32 v112, v127, v116
	v_cvt_pk_bf16_f32 v113, v113, v118
	v_cvt_pk_bf16_f32 v114, v151, v117
	v_cvt_pk_bf16_f32 v115, v124, v115
	global_store_dwordx4 v[122:123], v[112:115], off
	s_waitcnt vmcnt(7)
	v_fmamk_f32 v116, v229, 0x3a800000, v155
	v_rsq_f32_e32 v116, v116
	v_mov_b32_e32 v113, v100
	v_mov_b32_e32 v114, v104
	v_mov_b32_e32 v115, v96
	v_mov_b32_e32 v100, v109
	v_mov_b32_e32 v96, v105
	v_mov_b32_e32 v104, v110
	v_mov_b32_e32 v105, v102
	v_mov_b32_e32 v109, v98
	v_mov_b32_e32 v98, v107
	v_mov_b32_e32 v112, v108
	v_mov_b32_e32 v108, v106
	v_mov_b32_e32 v102, v111
	v_or_b32_e32 v106, 32, v150
	v_pk_mul_f32 v[100:101], v[100:101], v[116:117] op_sel_hi:[1,0]
	v_pk_mul_f32 v[96:97], v[96:97], v[116:117] op_sel_hi:[1,0]
	v_pk_mul_f32 v[104:105], v[104:105], v[116:117] op_sel_hi:[1,0]
	v_pk_mul_f32 v[98:99], v[98:99], v[116:117] op_sel_hi:[1,0]
	v_mad_i64_i32 v[110:111], s[24:25], v126, s49, v[120:121]
	v_ashrrev_i32_e32 v107, 31, v106
	v_pk_mul_f32 v[112:113], v[112:113], v[116:117] op_sel_hi:[1,0]
	v_pk_mul_f32 v[114:115], v[114:115], v[116:117] op_sel_hi:[1,0]
	v_pk_mul_f32 v[108:109], v[108:109], v[116:117] op_sel_hi:[1,0]
	v_pk_mul_f32 v[102:103], v[102:103], v[116:117] op_sel_hi:[1,0]
	v_mul_f32_e32 v117, 0xbfb8aa3b, v101
	v_mul_f32_e32 v122, 0xbfb8aa3b, v97
	v_mul_f32_e32 v123, 0xbfb8aa3b, v105
	v_mul_f32_e32 v126, 0xbfb8aa3b, v99
	v_lshl_add_u64 v[118:119], v[106:107], 2, s[6:7]
	v_mul_f32_e32 v107, 0xbfb8aa3b, v113
	v_mul_f32_e32 v116, 0xbfb8aa3b, v115
	v_mul_f32_e32 v124, 0xbfb8aa3b, v109
	v_mul_f32_e32 v125, 0xbfb8aa3b, v103
	v_exp_f32_e32 v117, v117
	v_exp_f32_e32 v122, v122
	v_exp_f32_e32 v123, v123
	v_exp_f32_e32 v126, v126
	v_exp_f32_e32 v107, v107
	v_exp_f32_e32 v116, v116
	v_exp_f32_e32 v124, v124
	v_exp_f32_e32 v125, v125
	v_add_f32_e32 v117, 1.0, v117
	v_add_f32_e32 v122, 1.0, v122
	v_add_f32_e32 v123, 1.0, v123
	v_add_f32_e32 v126, 1.0, v126
	v_add_f32_e32 v107, 1.0, v107
	v_add_f32_e32 v116, 1.0, v116
	v_add_f32_e32 v124, 1.0, v124
	v_add_f32_e32 v125, 1.0, v125
	v_rcp_f32_e32 v117, v117
	v_rcp_f32_e32 v122, v122
	v_rcp_f32_e32 v123, v123
	v_rcp_f32_e32 v126, v126
	v_rcp_f32_e32 v107, v107
	v_rcp_f32_e32 v116, v116
	v_rcp_f32_e32 v124, v124
	v_rcp_f32_e32 v125, v125
	v_lshl_add_u64 v[110:111], v[110:111], 0, s[22:23]
	v_lshl_add_u64 v[110:111], v[110:111], 0, s[0:1]
	v_mul_f32_e32 v101, v101, v117
	v_mul_f32_e32 v97, v97, v122
	v_mul_f32_e32 v105, v105, v123
	v_mul_f32_e32 v99, v99, v126
	v_lshl_add_u64 v[110:111], v[110:111], 0, v[140:141]
	v_mul_f32_e32 v107, v113, v107
	v_mul_f32_e32 v113, v115, v116
	v_mul_f32_e32 v109, v109, v124
	v_mul_f32_e32 v103, v103, v125
	v_mul_f32_e32 v100, v100, v101
	v_mul_f32_e32 v101, v96, v97
	v_mul_f32_e32 v97, v104, v105
	v_mul_f32_e32 v99, v98, v99
	v_mul_f32_e32 v107, v112, v107
	v_mul_f32_e32 v112, v114, v113
	v_mul_f32_e32 v104, v108, v109
	v_mul_f32_e32 v102, v102, v103
	v_cvt_pk_bf16_f32 v96, v107, v100
	v_cvt_pk_bf16_f32 v97, v97, v102
	v_cvt_pk_bf16_f32 v98, v112, v101
	v_cvt_pk_bf16_f32 v99, v104, v99
	global_store_dwordx4 v[110:111], v[96:99], off
	s_waitcnt vmcnt(7)
; __device__ __forceinline__ float fast_sigmoid(float z) { return __builtin_amdgcn_rcpf(1.f + __builtin_amdgcn_exp2f(-z * L2E)); }
; __device__ __forceinline__ u32x4 pack8(f32x4 a, f32x4 b) { u32x4 w; w.x = cvt_pk_bf16(a[0], a[1]); w.y = cvt_pk_bf16(a[2], a[3]); w.z = cvt_pk_bf16(b[0], b[1]); w.w = cvt_pk_bf16(b[2], b[3]); return w; }
;     __device__ __forceinline__ void operator()(const f32x4 (&acc)[2][2][4][2], const pg8::Unit& u, int wr, int wc, int fr, int fq) const {
; #pragma unroll
;         for (int ai = 0; ai < 2; ++ai)
; #pragma unroll
;             for (int m = 0; m < 4; ++m) { const int row = u.pm * 256 + ai * 128 + wr * 64 + m * 16 + fr;
;                 const float rstd = __builtin_amdgcn_rsqf(rss[row] * (1.f / D) + EPS);
;                 f32x4 h0, h1;
; #pragma unroll
;                 for (int i = 0; i < 4; ++i) { const float g0 = acc[ai][0][m][0][i] * rstd, u0 = acc[ai][1][m][0][i] * rstd, g1 = acc[ai][0][m][1][i] * rstd, u1 = acc[ai][1][m][1][i] * rstd;
;                     h0[i] = g0 * fast_sigmoid(g0) * u0; h1[i] = g1 * fast_sigmoid(g1) * u1; }
;                 *(u32x4*)(HFF + (size_t)row * DFF + u.pn * 128 + wc * 32 + 8 * fq) = pack8(h0, h1); }
	v_fmamk_f32 v100, v230, 0x3a800000, v155
	v_rsq_f32_e32 v100, v100
	v_mov_b32_e32 v97, v84
	v_mov_b32_e32 v98, v88
	v_mov_b32_e32 v99, v80
	v_mov_b32_e32 v84, v93
	v_mov_b32_e32 v80, v89
	v_mov_b32_e32 v88, v94
	v_mov_b32_e32 v89, v86
	v_mov_b32_e32 v93, v82
	v_mov_b32_e32 v82, v91
	v_mov_b32_e32 v96, v92
	v_mov_b32_e32 v92, v90
	v_mov_b32_e32 v86, v95
	v_or_b32_e32 v90, 48, v150
	v_pk_mul_f32 v[84:85], v[84:85], v[100:101] op_sel_hi:[1,0]
	v_pk_mul_f32 v[80:81], v[80:81], v[100:101] op_sel_hi:[1,0]
	v_pk_mul_f32 v[88:89], v[88:89], v[100:101] op_sel_hi:[1,0]
	v_pk_mul_f32 v[82:83], v[82:83], v[100:101] op_sel_hi:[1,0]
	v_ashrrev_i32_e32 v91, 31, v90
	v_pk_mul_f32 v[96:97], v[96:97], v[100:101] op_sel_hi:[1,0]
	v_pk_mul_f32 v[98:99], v[98:99], v[100:101] op_sel_hi:[1,0]
	v_pk_mul_f32 v[92:93], v[92:93], v[100:101] op_sel_hi:[1,0]
	v_pk_mul_f32 v[86:87], v[86:87], v[100:101] op_sel_hi:[1,0]
	v_mul_f32_e32 v101, 0xbfb8aa3b, v85
	v_mul_f32_e32 v104, 0xbfb8aa3b, v81
	v_mul_f32_e32 v105, 0xbfb8aa3b, v89
	v_mul_f32_e32 v108, 0xbfb8aa3b, v83
	v_mad_i64_i32 v[94:95], s[24:25], v106, s49, v[120:121]
	v_lshl_add_u64 v[102:103], v[90:91], 2, s[6:7]
	v_mul_f32_e32 v91, 0xbfb8aa3b, v97
	v_mul_f32_e32 v100, 0xbfb8aa3b, v99
	v_mul_f32_e32 v106, 0xbfb8aa3b, v93
	v_mul_f32_e32 v107, 0xbfb8aa3b, v87
	v_exp_f32_e32 v101, v101
	v_exp_f32_e32 v104, v104
	v_exp_f32_e32 v105, v105
	v_exp_f32_e32 v108, v108
	v_exp_f32_e32 v91, v91
	v_exp_f32_e32 v100, v100
	v_exp_f32_e32 v106, v106
	v_exp_f32_e32 v107, v107
	v_add_f32_e32 v101, 1.0, v101
	v_add_f32_e32 v104, 1.0, v104
	v_add_f32_e32 v105, 1.0, v105
	v_add_f32_e32 v108, 1.0, v108
	v_add_f32_e32 v91, 1.0, v91
	v_add_f32_e32 v100, 1.0, v100
	v_add_f32_e32 v106, 1.0, v106
	v_add_f32_e32 v107, 1.0, v107
	v_rcp_f32_e32 v101, v101
	v_rcp_f32_e32 v104, v104
	v_rcp_f32_e32 v105, v105
	v_rcp_f32_e32 v108, v108
	v_rcp_f32_e32 v91, v91
	v_rcp_f32_e32 v100, v100
	v_rcp_f32_e32 v106, v106
	v_rcp_f32_e32 v107, v107
	v_lshl_add_u64 v[94:95], v[94:95], 0, s[22:23]
	v_lshl_add_u64 v[94:95], v[94:95], 0, s[0:1]
	v_mul_f32_e32 v85, v85, v101
	v_mul_f32_e32 v81, v81, v104
	v_mul_f32_e32 v89, v89, v105
	v_mul_f32_e32 v83, v83, v108
	v_lshl_add_u64 v[94:95], v[94:95], 0, v[140:141]
	v_mul_f32_e32 v91, v97, v91
	v_mul_f32_e32 v97, v99, v100
	v_mul_f32_e32 v93, v93, v106
	v_mul_f32_e32 v87, v87, v107
	v_mul_f32_e32 v84, v84, v85
	v_mul_f32_e32 v85, v80, v81
	v_mul_f32_e32 v81, v88, v89
	v_mul_f32_e32 v83, v82, v83
	v_mul_f32_e32 v91, v96, v91
	v_mul_f32_e32 v96, v98, v97
	v_mul_f32_e32 v88, v92, v93
	v_mul_f32_e32 v86, v86, v87
	v_cvt_pk_bf16_f32 v80, v91, v84
	v_cvt_pk_bf16_f32 v81, v81, v86
	v_cvt_pk_bf16_f32 v82, v96, v85
	v_cvt_pk_bf16_f32 v83, v88, v83
	global_store_dwordx4 v[94:95], v[80:83], off
	s_waitcnt vmcnt(7)
	v_fmamk_f32 v84, v231, 0x3a800000, v155
	v_rsq_f32_e32 v84, v84
	v_mov_b32_e32 v81, v68
	v_mov_b32_e32 v82, v72
	v_mov_b32_e32 v83, v64
	v_mov_b32_e32 v68, v77
	v_mov_b32_e32 v64, v73
	v_mov_b32_e32 v72, v78
	v_mov_b32_e32 v73, v70
	v_mov_b32_e32 v77, v66
	v_mov_b32_e32 v66, v75
	v_mov_b32_e32 v80, v76
	v_mov_b32_e32 v76, v74
	v_mov_b32_e32 v70, v79
	v_add_u32_e32 v74, 0x80, v150
	v_pk_mul_f32 v[68:69], v[68:69], v[84:85] op_sel_hi:[1,0]
	v_pk_mul_f32 v[64:65], v[64:65], v[84:85] op_sel_hi:[1,0]
	v_pk_mul_f32 v[72:73], v[72:73], v[84:85] op_sel_hi:[1,0]
	v_pk_mul_f32 v[66:67], v[66:67], v[84:85] op_sel_hi:[1,0]
	v_ashrrev_i32_e32 v75, 31, v74
	v_pk_mul_f32 v[80:81], v[80:81], v[84:85] op_sel_hi:[1,0]
	v_pk_mul_f32 v[82:83], v[82:83], v[84:85] op_sel_hi:[1,0]
	v_pk_mul_f32 v[76:77], v[76:77], v[84:85] op_sel_hi:[1,0]
	v_pk_mul_f32 v[70:71], v[70:71], v[84:85] op_sel_hi:[1,0]
	v_mul_f32_e32 v85, 0xbfb8aa3b, v69
	v_mul_f32_e32 v88, 0xbfb8aa3b, v65
	v_mul_f32_e32 v89, 0xbfb8aa3b, v73
	v_mul_f32_e32 v92, 0xbfb8aa3b, v67
	v_mad_i64_i32 v[78:79], s[24:25], v90, s49, v[120:121]
	v_lshl_add_u64 v[86:87], v[74:75], 2, s[6:7]
	v_mul_f32_e32 v75, 0xbfb8aa3b, v81
	v_mul_f32_e32 v84, 0xbfb8aa3b, v83
	v_mul_f32_e32 v90, 0xbfb8aa3b, v77
	v_mul_f32_e32 v91, 0xbfb8aa3b, v71
	v_exp_f32_e32 v85, v85
	v_exp_f32_e32 v88, v88
	v_exp_f32_e32 v89, v89
	v_exp_f32_e32 v92, v92
	v_exp_f32_e32 v75, v75
	v_exp_f32_e32 v84, v84
	v_exp_f32_e32 v90, v90
	v_exp_f32_e32 v91, v91
	v_add_f32_e32 v85, 1.0, v85
	v_add_f32_e32 v88, 1.0, v88
	v_add_f32_e32 v89, 1.0, v89
	v_add_f32_e32 v92, 1.0, v92
	v_add_f32_e32 v75, 1.0, v75
	v_add_f32_e32 v84, 1.0, v84
	v_add_f32_e32 v90, 1.0, v90
	v_add_f32_e32 v91, 1.0, v91
	v_rcp_f32_e32 v85, v85
	v_rcp_f32_e32 v88, v88
	v_rcp_f32_e32 v89, v89
	v_rcp_f32_e32 v92, v92
	v_rcp_f32_e32 v75, v75
	v_rcp_f32_e32 v84, v84
	v_rcp_f32_e32 v90, v90
	v_rcp_f32_e32 v91, v91
	v_lshl_add_u64 v[78:79], v[78:79], 0, s[22:23]
	v_lshl_add_u64 v[78:79], v[78:79], 0, s[0:1]
	v_mul_f32_e32 v69, v69, v85
	v_mul_f32_e32 v65, v65, v88
	v_mul_f32_e32 v73, v73, v89
	v_mul_f32_e32 v67, v67, v92
	v_lshl_add_u64 v[78:79], v[78:79], 0, v[140:141]
	v_mul_f32_e32 v75, v81, v75
	v_mul_f32_e32 v81, v83, v84
	v_mul_f32_e32 v77, v77, v90
	v_mul_f32_e32 v71, v71, v91
	v_mul_f32_e32 v68, v68, v69
	v_mul_f32_e32 v69, v64, v65
	v_mul_f32_e32 v65, v72, v73
	v_mul_f32_e32 v67, v66, v67
	v_mul_f32_e32 v75, v80, v75
	v_mul_f32_e32 v80, v82, v81
	v_mul_f32_e32 v72, v76, v77
	v_mul_f32_e32 v70, v70, v71
	v_cvt_pk_bf16_f32 v64, v75, v68
	v_cvt_pk_bf16_f32 v65, v65, v70
	v_cvt_pk_bf16_f32 v66, v80, v69
	v_cvt_pk_bf16_f32 v67, v72, v67
	global_store_dwordx4 v[78:79], v[64:67], off
	s_waitcnt vmcnt(7)
; __device__ __forceinline__ float fast_sigmoid(float z) { return __builtin_amdgcn_rcpf(1.f + __builtin_amdgcn_exp2f(-z * L2E)); }
; __device__ __forceinline__ u32x4 pack8(f32x4 a, f32x4 b) { u32x4 w; w.x = cvt_pk_bf16(a[0], a[1]); w.y = cvt_pk_bf16(a[2], a[3]); w.z = cvt_pk_bf16(b[0], b[1]); w.w = cvt_pk_bf16(b[2], b[3]); return w; }
;     __device__ __forceinline__ void operator()(const f32x4 (&acc)[2][2][4][2], const pg8::Unit& u, int wr, int wc, int fr, int fq) const {
; #pragma unroll
;         for (int ai = 0; ai < 2; ++ai)
; #pragma unroll
;             for (int m = 0; m < 4; ++m) { const int row = u.pm * 256 + ai * 128 + wr * 64 + m * 16 + fr;
;                 const float rstd = __builtin_amdgcn_rsqf(rss[row] * (1.f / D) + EPS);
;                 f32x4 h0, h1;
; #pragma unroll
;                 for (int i = 0; i < 4; ++i) { const float g0 = acc[ai][0][m][0][i] * rstd, u0 = acc[ai][1][m][0][i] * rstd, g1 = acc[ai][0][m][1][i] * rstd, u1 = acc[ai][1][m][1][i] * rstd;
;                     h0[i] = g0 * fast_sigmoid(g0) * u0; h1[i] = g1 * fast_sigmoid(g1) * u1; }
;                 *(u32x4*)(HFF + (size_t)row * DFF + u.pn * 128 + wc * 32 + 8 * fq) = pack8(h0, h1); }
	v_fmamk_f32 v68, v232, 0x3a800000, v155
	v_rsq_f32_e32 v68, v68
	v_mov_b32_e32 v65, v52
	v_mov_b32_e32 v66, v56
	v_mov_b32_e32 v67, v48
	v_mov_b32_e32 v52, v61
	v_mov_b32_e32 v48, v57
	v_mov_b32_e32 v56, v62
	v_mov_b32_e32 v57, v54
	v_mov_b32_e32 v61, v50
	v_mov_b32_e32 v50, v59
	v_mov_b32_e32 v64, v60
	v_mov_b32_e32 v60, v58
	v_mov_b32_e32 v54, v63
	v_add_u32_e32 v58, 0x90, v150
	v_pk_mul_f32 v[52:53], v[52:53], v[68:69] op_sel_hi:[1,0]
	v_pk_mul_f32 v[48:49], v[48:49], v[68:69] op_sel_hi:[1,0]
	v_pk_mul_f32 v[56:57], v[56:57], v[68:69] op_sel_hi:[1,0]
	v_pk_mul_f32 v[50:51], v[50:51], v[68:69] op_sel_hi:[1,0]
	v_ashrrev_i32_e32 v59, 31, v58
	v_pk_mul_f32 v[64:65], v[64:65], v[68:69] op_sel_hi:[1,0]
	v_pk_mul_f32 v[66:67], v[66:67], v[68:69] op_sel_hi:[1,0]
	v_pk_mul_f32 v[60:61], v[60:61], v[68:69] op_sel_hi:[1,0]
	v_pk_mul_f32 v[54:55], v[54:55], v[68:69] op_sel_hi:[1,0]
	v_mul_f32_e32 v69, 0xbfb8aa3b, v53
	v_mul_f32_e32 v72, 0xbfb8aa3b, v49
	v_mul_f32_e32 v73, 0xbfb8aa3b, v57
	v_mul_f32_e32 v76, 0xbfb8aa3b, v51
	v_mad_i64_i32 v[62:63], s[24:25], v74, s49, v[120:121]
	v_lshl_add_u64 v[70:71], v[58:59], 2, s[6:7]
	v_mul_f32_e32 v59, 0xbfb8aa3b, v65
	v_mul_f32_e32 v68, 0xbfb8aa3b, v67
	v_mul_f32_e32 v74, 0xbfb8aa3b, v61
	v_mul_f32_e32 v75, 0xbfb8aa3b, v55
	v_exp_f32_e32 v69, v69
	v_exp_f32_e32 v72, v72
	v_exp_f32_e32 v73, v73
	v_exp_f32_e32 v76, v76
	v_exp_f32_e32 v59, v59
	v_exp_f32_e32 v68, v68
	v_exp_f32_e32 v74, v74
	v_exp_f32_e32 v75, v75
	v_add_f32_e32 v69, 1.0, v69
	v_add_f32_e32 v72, 1.0, v72
	v_add_f32_e32 v73, 1.0, v73
	v_add_f32_e32 v76, 1.0, v76
	v_add_f32_e32 v59, 1.0, v59
	v_add_f32_e32 v68, 1.0, v68
	v_add_f32_e32 v74, 1.0, v74
	v_add_f32_e32 v75, 1.0, v75
	v_rcp_f32_e32 v69, v69
	v_rcp_f32_e32 v72, v72
	v_rcp_f32_e32 v73, v73
	v_rcp_f32_e32 v76, v76
	v_rcp_f32_e32 v59, v59
	v_rcp_f32_e32 v68, v68
	v_rcp_f32_e32 v74, v74
	v_rcp_f32_e32 v75, v75
	v_lshl_add_u64 v[62:63], v[62:63], 0, s[22:23]
	v_lshl_add_u64 v[62:63], v[62:63], 0, s[0:1]
	v_mul_f32_e32 v53, v53, v69
	v_mul_f32_e32 v49, v49, v72
	v_mul_f32_e32 v57, v57, v73
	v_mul_f32_e32 v51, v51, v76
	v_lshl_add_u64 v[62:63], v[62:63], 0, v[140:141]
	v_mul_f32_e32 v59, v65, v59
	v_mul_f32_e32 v65, v67, v68
	v_mul_f32_e32 v61, v61, v74
	v_mul_f32_e32 v55, v55, v75
	v_mul_f32_e32 v52, v52, v53
	v_mul_f32_e32 v53, v48, v49
	v_mul_f32_e32 v49, v56, v57
	v_mul_f32_e32 v51, v50, v51
	v_mul_f32_e32 v59, v64, v59
	v_mul_f32_e32 v64, v66, v65
	v_mul_f32_e32 v56, v60, v61
	v_mul_f32_e32 v54, v54, v55
	v_cvt_pk_bf16_f32 v48, v59, v52
	v_cvt_pk_bf16_f32 v49, v49, v54
	v_cvt_pk_bf16_f32 v50, v64, v53
	v_cvt_pk_bf16_f32 v51, v56, v51
	global_store_dwordx4 v[62:63], v[48:51], off
	s_waitcnt vmcnt(7)
	v_fmamk_f32 v52, v233, 0x3a800000, v155
	v_rsq_f32_e32 v52, v52
	v_mov_b32_e32 v49, v36
	v_mov_b32_e32 v50, v40
	v_mov_b32_e32 v51, v32
	v_mov_b32_e32 v36, v45
	v_mov_b32_e32 v32, v41
	v_mov_b32_e32 v40, v46
	v_mov_b32_e32 v41, v38
	v_mov_b32_e32 v45, v34
	v_mov_b32_e32 v34, v43
	v_mov_b32_e32 v48, v44
	v_mov_b32_e32 v44, v42
	v_mov_b32_e32 v38, v47
	v_add_u32_e32 v42, 0xa0, v150
	v_pk_mul_f32 v[36:37], v[36:37], v[52:53] op_sel_hi:[1,0]
	v_pk_mul_f32 v[32:33], v[32:33], v[52:53] op_sel_hi:[1,0]
	v_pk_mul_f32 v[40:41], v[40:41], v[52:53] op_sel_hi:[1,0]
	v_pk_mul_f32 v[34:35], v[34:35], v[52:53] op_sel_hi:[1,0]
	v_ashrrev_i32_e32 v43, 31, v42
	v_pk_mul_f32 v[48:49], v[48:49], v[52:53] op_sel_hi:[1,0]
	v_pk_mul_f32 v[50:51], v[50:51], v[52:53] op_sel_hi:[1,0]
	v_pk_mul_f32 v[44:45], v[44:45], v[52:53] op_sel_hi:[1,0]
	v_pk_mul_f32 v[38:39], v[38:39], v[52:53] op_sel_hi:[1,0]
	v_mul_f32_e32 v53, 0xbfb8aa3b, v37
	v_mul_f32_e32 v56, 0xbfb8aa3b, v33
	v_mul_f32_e32 v57, 0xbfb8aa3b, v41
	v_mul_f32_e32 v60, 0xbfb8aa3b, v35
	v_mad_i64_i32 v[46:47], s[24:25], v58, s49, v[120:121]
	v_lshl_add_u64 v[54:55], v[42:43], 2, s[6:7]
	v_mul_f32_e32 v43, 0xbfb8aa3b, v49
	v_mul_f32_e32 v52, 0xbfb8aa3b, v51
	v_mul_f32_e32 v58, 0xbfb8aa3b, v45
	v_mul_f32_e32 v59, 0xbfb8aa3b, v39
	v_exp_f32_e32 v53, v53
	v_exp_f32_e32 v56, v56
	v_exp_f32_e32 v57, v57
	v_exp_f32_e32 v60, v60
	v_exp_f32_e32 v43, v43
	v_exp_f32_e32 v52, v52
	v_exp_f32_e32 v58, v58
	v_exp_f32_e32 v59, v59
	v_add_f32_e32 v53, 1.0, v53
	v_add_f32_e32 v56, 1.0, v56
	v_add_f32_e32 v57, 1.0, v57
	v_add_f32_e32 v60, 1.0, v60
	v_add_f32_e32 v43, 1.0, v43
	v_add_f32_e32 v52, 1.0, v52
	v_add_f32_e32 v58, 1.0, v58
	v_add_f32_e32 v59, 1.0, v59
	v_rcp_f32_e32 v53, v53
	v_rcp_f32_e32 v56, v56
	v_rcp_f32_e32 v57, v57
	v_rcp_f32_e32 v60, v60
	v_rcp_f32_e32 v43, v43
	v_rcp_f32_e32 v52, v52
	v_rcp_f32_e32 v58, v58
	v_rcp_f32_e32 v59, v59
	v_lshl_add_u64 v[46:47], v[46:47], 0, s[22:23]
	v_lshl_add_u64 v[46:47], v[46:47], 0, s[0:1]
	v_mul_f32_e32 v37, v37, v53
	v_mul_f32_e32 v33, v33, v56
	v_mul_f32_e32 v41, v41, v57
	v_mul_f32_e32 v35, v35, v60
	v_lshl_add_u64 v[46:47], v[46:47], 0, v[140:141]
	v_mul_f32_e32 v43, v49, v43
	v_mul_f32_e32 v49, v51, v52
	v_mul_f32_e32 v45, v45, v58
	v_mul_f32_e32 v39, v39, v59
	v_mul_f32_e32 v36, v36, v37
	v_mul_f32_e32 v37, v32, v33
	v_mul_f32_e32 v33, v40, v41
	v_mul_f32_e32 v35, v34, v35
	v_mul_f32_e32 v43, v48, v43
	v_mul_f32_e32 v48, v50, v49
	v_mul_f32_e32 v40, v44, v45
	v_mul_f32_e32 v38, v38, v39
	v_cvt_pk_bf16_f32 v32, v43, v36
	v_cvt_pk_bf16_f32 v33, v33, v38
	v_cvt_pk_bf16_f32 v34, v48, v37
	v_cvt_pk_bf16_f32 v35, v40, v35
	global_store_dwordx4 v[46:47], v[32:35], off
	s_waitcnt vmcnt(7)
; __device__ __forceinline__ float fast_sigmoid(float z) { return __builtin_amdgcn_rcpf(1.f + __builtin_amdgcn_exp2f(-z * L2E)); }
; __device__ __forceinline__ u32x4 pack8(f32x4 a, f32x4 b) { u32x4 w; w.x = cvt_pk_bf16(a[0], a[1]); w.y = cvt_pk_bf16(a[2], a[3]); w.z = cvt_pk_bf16(b[0], b[1]); w.w = cvt_pk_bf16(b[2], b[3]); return w; }
;     __device__ __forceinline__ void operator()(const f32x4 (&acc)[2][2][4][2], const pg8::Unit& u, int wr, int wc, int fr, int fq) const {
; #pragma unroll
;         for (int ai = 0; ai < 2; ++ai)
; #pragma unroll
;             for (int m = 0; m < 4; ++m) { const int row = u.pm * 256 + ai * 128 + wr * 64 + m * 16 + fr;
;                 const float rstd = __builtin_amdgcn_rsqf(rss[row] * (1.f / D) + EPS);
;                 f32x4 h0, h1;
; #pragma unroll
;                 for (int i = 0; i < 4; ++i) { const float g0 = acc[ai][0][m][0][i] * rstd, u0 = acc[ai][1][m][0][i] * rstd, g1 = acc[ai][0][m][1][i] * rstd, u1 = acc[ai][1][m][1][i] * rstd;
;                     h0[i] = g0 * fast_sigmoid(g0) * u0; h1[i] = g1 * fast_sigmoid(g1) * u1; }
;                 *(u32x4*)(HFF + (size_t)row * DFF + u.pn * 128 + wc * 32 + 8 * fq) = pack8(h0, h1); }
	v_fmamk_f32 v36, v234, 0x3a800000, v155
	v_rsq_f32_e32 v36, v36
	v_mov_b32_e32 v33, v20
	v_mov_b32_e32 v34, v24
	v_mov_b32_e32 v35, v16
	v_mov_b32_e32 v20, v29
	v_mov_b32_e32 v16, v25
	v_mov_b32_e32 v24, v30
	v_mov_b32_e32 v25, v22
	v_mov_b32_e32 v29, v18
	v_mov_b32_e32 v18, v27
	v_mov_b32_e32 v32, v28
	v_mov_b32_e32 v28, v26
	v_mov_b32_e32 v22, v31
	v_add_u32_e32 v26, 0xb0, v150
	v_pk_mul_f32 v[20:21], v[20:21], v[36:37] op_sel_hi:[1,0]
	v_pk_mul_f32 v[16:17], v[16:17], v[36:37] op_sel_hi:[1,0]
	v_pk_mul_f32 v[24:25], v[24:25], v[36:37] op_sel_hi:[1,0]
	v_pk_mul_f32 v[18:19], v[18:19], v[36:37] op_sel_hi:[1,0]
	v_ashrrev_i32_e32 v27, 31, v26
	v_pk_mul_f32 v[32:33], v[32:33], v[36:37] op_sel_hi:[1,0]
	v_pk_mul_f32 v[34:35], v[34:35], v[36:37] op_sel_hi:[1,0]
	v_pk_mul_f32 v[28:29], v[28:29], v[36:37] op_sel_hi:[1,0]
	v_pk_mul_f32 v[22:23], v[22:23], v[36:37] op_sel_hi:[1,0]
	v_mul_f32_e32 v37, 0xbfb8aa3b, v21
	v_mul_f32_e32 v40, 0xbfb8aa3b, v17
	v_mul_f32_e32 v41, 0xbfb8aa3b, v25
	v_mul_f32_e32 v44, 0xbfb8aa3b, v19
	v_mad_i64_i32 v[30:31], s[24:25], v42, s49, v[120:121]
	v_lshl_add_u64 v[38:39], v[26:27], 2, s[6:7]
	v_mul_f32_e32 v27, 0xbfb8aa3b, v33
	v_mul_f32_e32 v36, 0xbfb8aa3b, v35
	v_mul_f32_e32 v42, 0xbfb8aa3b, v29
	v_mul_f32_e32 v43, 0xbfb8aa3b, v23
	v_exp_f32_e32 v37, v37
	v_exp_f32_e32 v40, v40
	v_exp_f32_e32 v41, v41
	v_exp_f32_e32 v44, v44
	v_exp_f32_e32 v27, v27
	v_exp_f32_e32 v36, v36
	v_exp_f32_e32 v42, v42
	v_exp_f32_e32 v43, v43
	v_add_f32_e32 v37, 1.0, v37
	v_add_f32_e32 v40, 1.0, v40
	v_add_f32_e32 v41, 1.0, v41
	v_add_f32_e32 v44, 1.0, v44
	v_add_f32_e32 v27, 1.0, v27
	v_add_f32_e32 v36, 1.0, v36
	v_add_f32_e32 v42, 1.0, v42
	v_add_f32_e32 v43, 1.0, v43
	v_rcp_f32_e32 v37, v37
	v_rcp_f32_e32 v40, v40
	v_rcp_f32_e32 v41, v41
	v_rcp_f32_e32 v44, v44
	v_rcp_f32_e32 v27, v27
	v_rcp_f32_e32 v36, v36
	v_rcp_f32_e32 v42, v42
	v_rcp_f32_e32 v43, v43
	v_lshl_add_u64 v[30:31], v[30:31], 0, s[22:23]
	v_lshl_add_u64 v[30:31], v[30:31], 0, s[0:1]
	v_mul_f32_e32 v21, v21, v37
	v_mul_f32_e32 v17, v17, v40
	v_mul_f32_e32 v25, v25, v41
	v_mul_f32_e32 v19, v19, v44
	v_lshl_add_u64 v[30:31], v[30:31], 0, v[140:141]
	v_mul_f32_e32 v27, v33, v27
	v_mul_f32_e32 v33, v35, v36
	v_mul_f32_e32 v29, v29, v42
	v_mul_f32_e32 v23, v23, v43
	v_mul_f32_e32 v20, v20, v21
	v_mul_f32_e32 v21, v16, v17
	v_mul_f32_e32 v17, v24, v25
	v_mul_f32_e32 v19, v18, v19
	v_mul_f32_e32 v27, v32, v27
	v_mul_f32_e32 v32, v34, v33
	v_mul_f32_e32 v24, v28, v29
	v_mul_f32_e32 v22, v22, v23
	v_cvt_pk_bf16_f32 v16, v27, v20
	v_cvt_pk_bf16_f32 v17, v17, v22
	v_cvt_pk_bf16_f32 v18, v32, v21
	v_cvt_pk_bf16_f32 v19, v24, v19
	global_store_dwordx4 v[30:31], v[16:19], off
	s_nop 0
	v_mov_b32_e32 v18, v8
	v_mov_b32_e32 v8, v14
	v_mov_b32_e32 v17, v4
	v_mov_b32_e32 v19, v0
	v_mov_b32_e32 v4, v13
	v_mov_b32_e32 v0, v9
	v_mov_b32_e32 v9, v6
	v_mov_b32_e32 v13, v2
	v_mov_b32_e32 v2, v11
	v_mov_b32_e32 v16, v12
	v_mov_b32_e32 v12, v10
	v_mov_b32_e32 v6, v15
	v_mad_i64_i32 v[10:11], s[24:25], v26, s49, v[120:121]
	v_lshl_add_u64 v[10:11], v[10:11], 0, s[22:23]
	v_lshl_add_u64 v[10:11], v[10:11], 0, s[0:1]
	v_lshl_add_u64 v[10:11], v[10:11], 0, v[140:141]
	s_waitcnt vmcnt(7)
	v_fmamk_f32 v14, v235, 0x3a800000, v155
	v_rsq_f32_e32 v14, v14
	s_nop 0
	v_pk_mul_f32 v[4:5], v[4:5], v[14:15] op_sel_hi:[1,0]
	v_pk_mul_f32 v[0:1], v[0:1], v[14:15] op_sel_hi:[1,0]
	v_pk_mul_f32 v[8:9], v[8:9], v[14:15] op_sel_hi:[1,0]
	v_pk_mul_f32 v[2:3], v[2:3], v[14:15] op_sel_hi:[1,0]
	v_pk_mul_f32 v[16:17], v[16:17], v[14:15] op_sel_hi:[1,0]
	v_pk_mul_f32 v[18:19], v[18:19], v[14:15] op_sel_hi:[1,0]
	v_pk_mul_f32 v[12:13], v[12:13], v[14:15] op_sel_hi:[1,0]
	v_pk_mul_f32 v[6:7], v[6:7], v[14:15] op_sel_hi:[1,0]
	v_mul_f32_e32 v20, 0xbfb8aa3b, v5
	v_mul_f32_e32 v21, 0xbfb8aa3b, v1
	v_mul_f32_e32 v22, 0xbfb8aa3b, v9
	v_mul_f32_e32 v25, 0xbfb8aa3b, v3
	v_mul_f32_e32 v14, 0xbfb8aa3b, v17
	v_mul_f32_e32 v15, 0xbfb8aa3b, v19
	v_mul_f32_e32 v23, 0xbfb8aa3b, v13
	v_mul_f32_e32 v24, 0xbfb8aa3b, v7
	v_exp_f32_e32 v20, v20
	v_exp_f32_e32 v21, v21
	v_exp_f32_e32 v22, v22
	v_exp_f32_e32 v25, v25
	v_exp_f32_e32 v14, v14
	v_exp_f32_e32 v15, v15
	v_exp_f32_e32 v23, v23
	v_exp_f32_e32 v24, v24
	v_add_f32_e32 v20, 1.0, v20
	v_add_f32_e32 v21, 1.0, v21
	v_add_f32_e32 v22, 1.0, v22
	v_add_f32_e32 v25, 1.0, v25
	v_add_f32_e32 v14, 1.0, v14
	v_add_f32_e32 v15, 1.0, v15
	v_add_f32_e32 v23, 1.0, v23
	v_add_f32_e32 v24, 1.0, v24
	v_rcp_f32_e32 v20, v20
	v_rcp_f32_e32 v21, v21
	v_rcp_f32_e32 v22, v22
	v_rcp_f32_e32 v25, v25
	v_rcp_f32_e32 v14, v14
	v_rcp_f32_e32 v15, v15
	v_rcp_f32_e32 v23, v23
	v_rcp_f32_e32 v24, v24
	v_mul_f32_e32 v5, v5, v20
	v_mul_f32_e32 v1, v1, v21
	v_mul_f32_e32 v9, v9, v22
	v_mul_f32_e32 v3, v3, v25
	v_mul_f32_e32 v14, v17, v14
	v_mul_f32_e32 v15, v19, v15
	v_mul_f32_e32 v13, v13, v23
	v_mul_f32_e32 v7, v7, v24
	v_mul_f32_e32 v4, v4, v5
	v_mul_f32_e32 v5, v0, v1
	v_mul_f32_e32 v1, v8, v9
	v_mul_f32_e32 v3, v2, v3
	v_mul_f32_e32 v14, v16, v14
	v_mul_f32_e32 v15, v18, v15
	v_mul_f32_e32 v8, v12, v13
	v_mul_f32_e32 v6, v6, v7
	v_cvt_pk_bf16_f32 v0, v14, v4
	v_cvt_pk_bf16_f32 v1, v1, v6
	v_cvt_pk_bf16_f32 v2, v15, v5
	v_cvt_pk_bf16_f32 v3, v8, v3
	global_store_dwordx4 v[10:11], v[0:3], off
	s_cbranch_vccnz .LBB0_852
	s_andn2_b64 vcc, exec, s[4:5]
	s_cbranch_vccnz .LBB0_851
	s_barrier
	s_branch .LBB0_851
